# fused phase first-branch units: epilogue variant that does not fetch the unused partial-sum tile (half the epilogue loads)
# speedup vs baseline: 1.0030x; 1.0011x over previous
; __device__ __forceinline__ unsigned cvtpk(float lo, float hi) { f32x2 v = {lo, hi}; bf16x2_t b = __builtin_convertvector(v, bf16x2_t); return __builtin_bit_cast(unsigned, b); }
; __device__ __forceinline__ float bflo(unsigned u) { return __uint_as_float(u << 16); }
; __device__ __forceinline__ float bfhi(unsigned u) { return __uint_as_float(u & 0xffff0000u); }
;     __device__ __forceinline__ void operator()(const f32x4 (&acc)[2][2][4][2], const Unit& u, int wr, int wc, int fr, int fq) const {
;     ...
;                         if (mode == 6) {
;                             const u32x4 gq = *(const u32x4*)(sG + rl * 256 + cl);
;                             v0[0] *= bflo(gq.x); v0[1] *= bfhi(gq.x); v0[2] *= bflo(gq.y); v0[3] *= bfhi(gq.y); v1[0] *= bflo(gq.z); v1[1] *= bfhi(gq.z); v1[2] *= bflo(gq.w); v1[3] *= bfhi(gq.w);
;                             if (u.br > 0) { const u32x4 mo = *(const u32x4*)(sM + rl * 256 + cl);
;                                 v0[0] += bflo(mo.x); v0[1] += bfhi(mo.x); v0[2] += bflo(mo.y); v0[3] += bfhi(mo.y); v1[0] += bflo(mo.z); v1[1] += bfhi(mo.z); v1[2] += bflo(mo.w); v1[3] += bfhi(mo.w); } }
;                         u32x4 w; w.x = cvtpk(v0[0], v0[1]); w.y = cvtpk(v0[2], v0[3]); w.z = cvtpk(v1[0], v1[1]); w.w = cvtpk(v1[2], v1[3]);
;                         if (mode == 5) *(u32x4*)(sG + rl * 256 + cl) = w;
;                         else if (mode == 6 && u.br < 2) *(u32x4*)(sM + rl * 256 + cl) = w;
.Lepi6z:
	v_lshlrev_b32_e32 v228, 9, v184
	v_lshl_add_u32 v228, v150, 1, v228
	v_readlane_b32 s74, v252, 54
	v_readlane_b32 s75, v252, 55
	v_readlane_b32 s76, v252, 56
	v_readlane_b32 s77, v252, 57
	s_nop 3
	s_mov_b32 s90, s76
	s_mov_b32 s91, s77
	s_mov_b32 s82, s74
	s_mov_b32 s83, s75
	global_load_dwordx4 v[136:139], v228, s[82:83]
	global_load_dwordx4 v[140:143], v228, s[82:83] offset:256
	s_add_u32 s82, s74, 0x2000
	s_addc_u32 s83, s75, 0
	global_load_dwordx4 v[162:165], v228, s[82:83]
	global_load_dwordx4 v[166:169], v228, s[82:83] offset:256
	s_add_u32 s82, s74, 0x4000
	s_addc_u32 s83, s75, 0
	global_load_dwordx4 v[170:173], v228, s[82:83]
	global_load_dwordx4 v[174:177], v228, s[82:83] offset:256
	s_add_u32 s82, s74, 0x6000
	s_addc_u32 s83, s75, 0
	global_load_dwordx4 v[186:189], v228, s[82:83]
	global_load_dwordx4 v[190:193], v228, s[82:83] offset:256
	s_waitcnt vmcnt(7)
	v_lshlrev_b32_e32 v250, 16, v136
	v_and_b32_e32 v251, 0xffff0000, v136
	v_pk_mul_f32 v[132:133], v[132:133], v[250:251]
	v_lshlrev_b32_e32 v250, 16, v137
	v_and_b32_e32 v251, 0xffff0000, v137
	v_pk_mul_f32 v[134:135], v[134:135], v[250:251]
	v_lshlrev_b32_e32 v250, 16, v138
	v_and_b32_e32 v251, 0xffff0000, v138
	v_pk_mul_f32 v[128:129], v[128:129], v[250:251]
	v_lshlrev_b32_e32 v250, 16, v139
	v_and_b32_e32 v251, 0xffff0000, v139
	v_pk_mul_f32 v[130:131], v[130:131], v[250:251]
	v_cvt_pk_bf16_f32 v246, v132, v133
	v_cvt_pk_bf16_f32 v247, v134, v135
	v_cvt_pk_bf16_f32 v248, v128, v129
	v_cvt_pk_bf16_f32 v249, v130, v131
	global_store_dwordx4 v228, v[246:249], s[90:91]
	s_add_u32 s82, s74, 0x10000
	s_addc_u32 s83, s75, 0
	global_load_dwordx4 v[136:139], v228, s[82:83]
	s_waitcnt vmcnt(8)
	v_lshlrev_b32_e32 v250, 16, v140
	v_and_b32_e32 v251, 0xffff0000, v140
	v_pk_mul_f32 v[100:101], v[100:101], v[250:251]
	v_lshlrev_b32_e32 v250, 16, v141
	v_and_b32_e32 v251, 0xffff0000, v141
	v_pk_mul_f32 v[102:103], v[102:103], v[250:251]
	v_lshlrev_b32_e32 v250, 16, v142
	v_and_b32_e32 v251, 0xffff0000, v142
	v_pk_mul_f32 v[96:97], v[96:97], v[250:251]
	v_lshlrev_b32_e32 v250, 16, v143
	v_and_b32_e32 v251, 0xffff0000, v143
	v_pk_mul_f32 v[98:99], v[98:99], v[250:251]
	v_cvt_pk_bf16_f32 v210, v100, v101
	v_cvt_pk_bf16_f32 v211, v102, v103
	v_cvt_pk_bf16_f32 v212, v96, v97
	v_cvt_pk_bf16_f32 v213, v98, v99
	global_store_dwordx4 v228, v[210:213], s[90:91] offset:256
	s_add_u32 s90, s90, 0x2000
	s_addc_u32 s91, s91, 0
	global_load_dwordx4 v[140:143], v228, s[82:83] offset:256
	s_waitcnt vmcnt(9)
	v_lshlrev_b32_e32 v250, 16, v162
	v_and_b32_e32 v251, 0xffff0000, v162
	v_pk_mul_f32 v[124:125], v[124:125], v[250:251]
	v_lshlrev_b32_e32 v250, 16, v163
	v_and_b32_e32 v251, 0xffff0000, v163
	v_pk_mul_f32 v[126:127], v[126:127], v[250:251]
	v_lshlrev_b32_e32 v250, 16, v164
	v_and_b32_e32 v251, 0xffff0000, v164
	v_pk_mul_f32 v[120:121], v[120:121], v[250:251]
	v_lshlrev_b32_e32 v250, 16, v165
	v_and_b32_e32 v251, 0xffff0000, v165
	v_pk_mul_f32 v[122:123], v[122:123], v[250:251]
	v_cvt_pk_bf16_f32 v246, v124, v125
	v_cvt_pk_bf16_f32 v247, v126, v127
	v_cvt_pk_bf16_f32 v248, v120, v121
	v_cvt_pk_bf16_f32 v249, v122, v123
	global_store_dwordx4 v228, v[246:249], s[90:91]
	s_add_u32 s82, s74, 0x12000
	s_addc_u32 s83, s75, 0
	global_load_dwordx4 v[162:165], v228, s[82:83]
	s_waitcnt vmcnt(10)
	v_lshlrev_b32_e32 v250, 16, v166
	v_and_b32_e32 v251, 0xffff0000, v166
	v_pk_mul_f32 v[92:93], v[92:93], v[250:251]
	v_lshlrev_b32_e32 v250, 16, v167
	v_and_b32_e32 v251, 0xffff0000, v167
	v_pk_mul_f32 v[94:95], v[94:95], v[250:251]
	v_lshlrev_b32_e32 v250, 16, v168
	v_and_b32_e32 v251, 0xffff0000, v168
	v_pk_mul_f32 v[88:89], v[88:89], v[250:251]
	v_lshlrev_b32_e32 v250, 16, v169
	v_and_b32_e32 v251, 0xffff0000, v169
	v_pk_mul_f32 v[90:91], v[90:91], v[250:251]
	v_cvt_pk_bf16_f32 v210, v92, v93
	v_cvt_pk_bf16_f32 v211, v94, v95
	v_cvt_pk_bf16_f32 v212, v88, v89
	v_cvt_pk_bf16_f32 v213, v90, v91
	global_store_dwordx4 v228, v[210:213], s[90:91] offset:256
	s_add_u32 s90, s90, 0x2000
	s_addc_u32 s91, s91, 0
	global_load_dwordx4 v[166:169], v228, s[82:83] offset:256
	s_waitcnt vmcnt(11)
	v_lshlrev_b32_e32 v250, 16, v170
	v_and_b32_e32 v251, 0xffff0000, v170
	v_pk_mul_f32 v[116:117], v[116:117], v[250:251]
	v_lshlrev_b32_e32 v250, 16, v171
	v_and_b32_e32 v251, 0xffff0000, v171
	v_pk_mul_f32 v[118:119], v[118:119], v[250:251]
	v_lshlrev_b32_e32 v250, 16, v172
	v_and_b32_e32 v251, 0xffff0000, v172
	v_pk_mul_f32 v[112:113], v[112:113], v[250:251]
	v_lshlrev_b32_e32 v250, 16, v173
	v_and_b32_e32 v251, 0xffff0000, v173
	v_pk_mul_f32 v[114:115], v[114:115], v[250:251]
	v_cvt_pk_bf16_f32 v246, v116, v117
	v_cvt_pk_bf16_f32 v247, v118, v119
	v_cvt_pk_bf16_f32 v248, v112, v113
	v_cvt_pk_bf16_f32 v249, v114, v115
	global_store_dwordx4 v228, v[246:249], s[90:91]
	s_add_u32 s82, s74, 0x14000
	s_addc_u32 s83, s75, 0
	global_load_dwordx4 v[170:173], v228, s[82:83]
	s_waitcnt vmcnt(12)
	v_lshlrev_b32_e32 v250, 16, v174
	v_and_b32_e32 v251, 0xffff0000, v174
	v_pk_mul_f32 v[84:85], v[84:85], v[250:251]
	v_lshlrev_b32_e32 v250, 16, v175
	v_and_b32_e32 v251, 0xffff0000, v175
	v_pk_mul_f32 v[86:87], v[86:87], v[250:251]
	v_lshlrev_b32_e32 v250, 16, v176
	v_and_b32_e32 v251, 0xffff0000, v176
	v_pk_mul_f32 v[80:81], v[80:81], v[250:251]
	v_lshlrev_b32_e32 v250, 16, v177
	v_and_b32_e32 v251, 0xffff0000, v177
	v_pk_mul_f32 v[82:83], v[82:83], v[250:251]
	v_cvt_pk_bf16_f32 v210, v84, v85
	v_cvt_pk_bf16_f32 v211, v86, v87
	v_cvt_pk_bf16_f32 v212, v80, v81
	v_cvt_pk_bf16_f32 v213, v82, v83
	global_store_dwordx4 v228, v[210:213], s[90:91] offset:256
	s_add_u32 s90, s90, 0x2000
	s_addc_u32 s91, s91, 0
	global_load_dwordx4 v[174:177], v228, s[82:83] offset:256
	s_waitcnt vmcnt(13)
; __device__ __forceinline__ unsigned cvtpk(float lo, float hi) { f32x2 v = {lo, hi}; bf16x2_t b = __builtin_convertvector(v, bf16x2_t); return __builtin_bit_cast(unsigned, b); }
; __device__ __forceinline__ float bflo(unsigned u) { return __uint_as_float(u << 16); }
; __device__ __forceinline__ float bfhi(unsigned u) { return __uint_as_float(u & 0xffff0000u); }
;     __device__ __forceinline__ void operator()(const f32x4 (&acc)[2][2][4][2], const Unit& u, int wr, int wc, int fr, int fq) const {
;     ...
;                         if (mode == 6) {
;                             const u32x4 gq = *(const u32x4*)(sG + rl * 256 + cl);
;                             v0[0] *= bflo(gq.x); v0[1] *= bfhi(gq.x); v0[2] *= bflo(gq.y); v0[3] *= bfhi(gq.y); v1[0] *= bflo(gq.z); v1[1] *= bfhi(gq.z); v1[2] *= bflo(gq.w); v1[3] *= bfhi(gq.w);
;                             if (u.br > 0) { const u32x4 mo = *(const u32x4*)(sM + rl * 256 + cl);
;                                 v0[0] += bflo(mo.x); v0[1] += bfhi(mo.x); v0[2] += bflo(mo.y); v0[3] += bfhi(mo.y); v1[0] += bflo(mo.z); v1[1] += bfhi(mo.z); v1[2] += bflo(mo.w); v1[3] += bfhi(mo.w); } }
;                         u32x4 w; w.x = cvtpk(v0[0], v0[1]); w.y = cvtpk(v0[2], v0[3]); w.z = cvtpk(v1[0], v1[1]); w.w = cvtpk(v1[2], v1[3]);
;                         if (mode == 5) *(u32x4*)(sG + rl * 256 + cl) = w;
;                         else if (mode == 6 && u.br < 2) *(u32x4*)(sM + rl * 256 + cl) = w;
	v_lshlrev_b32_e32 v250, 16, v186
	v_and_b32_e32 v251, 0xffff0000, v186
	v_pk_mul_f32 v[108:109], v[108:109], v[250:251]
	v_lshlrev_b32_e32 v250, 16, v187
	v_and_b32_e32 v251, 0xffff0000, v187
	v_pk_mul_f32 v[110:111], v[110:111], v[250:251]
	v_lshlrev_b32_e32 v250, 16, v188
	v_and_b32_e32 v251, 0xffff0000, v188
	v_pk_mul_f32 v[104:105], v[104:105], v[250:251]
	v_lshlrev_b32_e32 v250, 16, v189
	v_and_b32_e32 v251, 0xffff0000, v189
	v_pk_mul_f32 v[106:107], v[106:107], v[250:251]
	v_cvt_pk_bf16_f32 v246, v108, v109
	v_cvt_pk_bf16_f32 v247, v110, v111
	v_cvt_pk_bf16_f32 v248, v104, v105
	v_cvt_pk_bf16_f32 v249, v106, v107
	global_store_dwordx4 v228, v[246:249], s[90:91]
	s_add_u32 s82, s74, 0x16000
	s_addc_u32 s83, s75, 0
	global_load_dwordx4 v[186:189], v228, s[82:83]
	s_waitcnt vmcnt(14)
	v_lshlrev_b32_e32 v250, 16, v190
	v_and_b32_e32 v251, 0xffff0000, v190
	v_pk_mul_f32 v[76:77], v[76:77], v[250:251]
	v_lshlrev_b32_e32 v250, 16, v191
	v_and_b32_e32 v251, 0xffff0000, v191
	v_pk_mul_f32 v[78:79], v[78:79], v[250:251]
	v_lshlrev_b32_e32 v250, 16, v192
	v_and_b32_e32 v251, 0xffff0000, v192
	v_pk_mul_f32 v[72:73], v[72:73], v[250:251]
	v_lshlrev_b32_e32 v250, 16, v193
	v_and_b32_e32 v251, 0xffff0000, v193
	v_pk_mul_f32 v[74:75], v[74:75], v[250:251]
	v_cvt_pk_bf16_f32 v210, v76, v77
	v_cvt_pk_bf16_f32 v211, v78, v79
	v_cvt_pk_bf16_f32 v212, v72, v73
	v_cvt_pk_bf16_f32 v213, v74, v75
	global_store_dwordx4 v228, v[210:213], s[90:91] offset:256
	s_add_u32 s90, s76, 0x10000
	s_addc_u32 s91, s77, 0
	global_load_dwordx4 v[190:193], v228, s[82:83] offset:256
	s_waitcnt vmcnt(14)
	v_lshlrev_b32_e32 v250, 16, v136
	v_and_b32_e32 v251, 0xffff0000, v136
	v_pk_mul_f32 v[68:69], v[68:69], v[250:251]
	v_lshlrev_b32_e32 v250, 16, v137
	v_and_b32_e32 v251, 0xffff0000, v137
	v_pk_mul_f32 v[70:71], v[70:71], v[250:251]
	v_lshlrev_b32_e32 v250, 16, v138
	v_and_b32_e32 v251, 0xffff0000, v138
	v_pk_mul_f32 v[64:65], v[64:65], v[250:251]
	v_lshlrev_b32_e32 v250, 16, v139
	v_and_b32_e32 v251, 0xffff0000, v139
	v_pk_mul_f32 v[66:67], v[66:67], v[250:251]
	v_cvt_pk_bf16_f32 v246, v68, v69
	v_cvt_pk_bf16_f32 v247, v70, v71
	v_cvt_pk_bf16_f32 v248, v64, v65
	v_cvt_pk_bf16_f32 v249, v66, v67
	global_store_dwordx4 v228, v[246:249], s[90:91]
	s_waitcnt vmcnt(13)
	v_lshlrev_b32_e32 v250, 16, v140
	v_and_b32_e32 v251, 0xffff0000, v140
	v_pk_mul_f32 v[36:37], v[36:37], v[250:251]
	v_lshlrev_b32_e32 v250, 16, v141
	v_and_b32_e32 v251, 0xffff0000, v141
	v_pk_mul_f32 v[38:39], v[38:39], v[250:251]
	v_lshlrev_b32_e32 v250, 16, v142
	v_and_b32_e32 v251, 0xffff0000, v142
	v_pk_mul_f32 v[32:33], v[32:33], v[250:251]
	v_lshlrev_b32_e32 v250, 16, v143
	v_and_b32_e32 v251, 0xffff0000, v143
	v_pk_mul_f32 v[34:35], v[34:35], v[250:251]
	v_cvt_pk_bf16_f32 v210, v36, v37
	v_cvt_pk_bf16_f32 v211, v38, v39
	v_cvt_pk_bf16_f32 v212, v32, v33
	v_cvt_pk_bf16_f32 v213, v34, v35
	global_store_dwordx4 v228, v[210:213], s[90:91] offset:256
	s_add_u32 s90, s90, 0x2000
	s_addc_u32 s91, s91, 0
	s_waitcnt vmcnt(12)
	v_lshlrev_b32_e32 v250, 16, v162
	v_and_b32_e32 v251, 0xffff0000, v162
	v_pk_mul_f32 v[60:61], v[60:61], v[250:251]
	v_lshlrev_b32_e32 v250, 16, v163
	v_and_b32_e32 v251, 0xffff0000, v163
	v_pk_mul_f32 v[62:63], v[62:63], v[250:251]
	v_lshlrev_b32_e32 v250, 16, v164
	v_and_b32_e32 v251, 0xffff0000, v164
	v_pk_mul_f32 v[56:57], v[56:57], v[250:251]
	v_lshlrev_b32_e32 v250, 16, v165
	v_and_b32_e32 v251, 0xffff0000, v165
	v_pk_mul_f32 v[58:59], v[58:59], v[250:251]
	v_cvt_pk_bf16_f32 v246, v60, v61
	v_cvt_pk_bf16_f32 v247, v62, v63
	v_cvt_pk_bf16_f32 v248, v56, v57
	v_cvt_pk_bf16_f32 v249, v58, v59
	global_store_dwordx4 v228, v[246:249], s[90:91]
	s_waitcnt vmcnt(11)
; __device__ __forceinline__ unsigned cvtpk(float lo, float hi) { f32x2 v = {lo, hi}; bf16x2_t b = __builtin_convertvector(v, bf16x2_t); return __builtin_bit_cast(unsigned, b); }
; __device__ __forceinline__ float bflo(unsigned u) { return __uint_as_float(u << 16); }
; __device__ __forceinline__ float bfhi(unsigned u) { return __uint_as_float(u & 0xffff0000u); }
;     __device__ __forceinline__ void operator()(const f32x4 (&acc)[2][2][4][2], const Unit& u, int wr, int wc, int fr, int fq) const {
;     ...
;                         if (mode == 6) {
;                             const u32x4 gq = *(const u32x4*)(sG + rl * 256 + cl);
;                             v0[0] *= bflo(gq.x); v0[1] *= bfhi(gq.x); v0[2] *= bflo(gq.y); v0[3] *= bfhi(gq.y); v1[0] *= bflo(gq.z); v1[1] *= bfhi(gq.z); v1[2] *= bflo(gq.w); v1[3] *= bfhi(gq.w);
;                             if (u.br > 0) { const u32x4 mo = *(const u32x4*)(sM + rl * 256 + cl);
;                                 v0[0] += bflo(mo.x); v0[1] += bfhi(mo.x); v0[2] += bflo(mo.y); v0[3] += bfhi(mo.y); v1[0] += bflo(mo.z); v1[1] += bfhi(mo.z); v1[2] += bflo(mo.w); v1[3] += bfhi(mo.w); } }
;                         u32x4 w; w.x = cvtpk(v0[0], v0[1]); w.y = cvtpk(v0[2], v0[3]); w.z = cvtpk(v1[0], v1[1]); w.w = cvtpk(v1[2], v1[3]);
;                         if (mode == 5) *(u32x4*)(sG + rl * 256 + cl) = w;
;                         else if (mode == 6 && u.br < 2) *(u32x4*)(sM + rl * 256 + cl) = w;
	v_lshlrev_b32_e32 v250, 16, v166
	v_and_b32_e32 v251, 0xffff0000, v166
	v_pk_mul_f32 v[28:29], v[28:29], v[250:251]
	v_lshlrev_b32_e32 v250, 16, v167
	v_and_b32_e32 v251, 0xffff0000, v167
	v_pk_mul_f32 v[30:31], v[30:31], v[250:251]
	v_lshlrev_b32_e32 v250, 16, v168
	v_and_b32_e32 v251, 0xffff0000, v168
	v_pk_mul_f32 v[24:25], v[24:25], v[250:251]
	v_lshlrev_b32_e32 v250, 16, v169
	v_and_b32_e32 v251, 0xffff0000, v169
	v_pk_mul_f32 v[26:27], v[26:27], v[250:251]
	v_cvt_pk_bf16_f32 v210, v28, v29
	v_cvt_pk_bf16_f32 v211, v30, v31
	v_cvt_pk_bf16_f32 v212, v24, v25
	v_cvt_pk_bf16_f32 v213, v26, v27
	global_store_dwordx4 v228, v[210:213], s[90:91] offset:256
	s_add_u32 s90, s90, 0x2000
	s_addc_u32 s91, s91, 0
	s_waitcnt vmcnt(10)
	v_lshlrev_b32_e32 v250, 16, v170
	v_and_b32_e32 v251, 0xffff0000, v170
	v_pk_mul_f32 v[52:53], v[52:53], v[250:251]
	v_lshlrev_b32_e32 v250, 16, v171
	v_and_b32_e32 v251, 0xffff0000, v171
	v_pk_mul_f32 v[54:55], v[54:55], v[250:251]
	v_lshlrev_b32_e32 v250, 16, v172
	v_and_b32_e32 v251, 0xffff0000, v172
	v_pk_mul_f32 v[48:49], v[48:49], v[250:251]
	v_lshlrev_b32_e32 v250, 16, v173
	v_and_b32_e32 v251, 0xffff0000, v173
	v_pk_mul_f32 v[50:51], v[50:51], v[250:251]
	v_cvt_pk_bf16_f32 v246, v52, v53
	v_cvt_pk_bf16_f32 v247, v54, v55
	v_cvt_pk_bf16_f32 v248, v48, v49
	v_cvt_pk_bf16_f32 v249, v50, v51
	global_store_dwordx4 v228, v[246:249], s[90:91]
	s_waitcnt vmcnt(9)
	v_lshlrev_b32_e32 v250, 16, v174
	v_and_b32_e32 v251, 0xffff0000, v174
	v_pk_mul_f32 v[20:21], v[20:21], v[250:251]
	v_lshlrev_b32_e32 v250, 16, v175
	v_and_b32_e32 v251, 0xffff0000, v175
	v_pk_mul_f32 v[22:23], v[22:23], v[250:251]
	v_lshlrev_b32_e32 v250, 16, v176
	v_and_b32_e32 v251, 0xffff0000, v176
	v_pk_mul_f32 v[16:17], v[16:17], v[250:251]
	v_lshlrev_b32_e32 v250, 16, v177
	v_and_b32_e32 v251, 0xffff0000, v177
	v_pk_mul_f32 v[18:19], v[18:19], v[250:251]
	v_cvt_pk_bf16_f32 v210, v20, v21
	v_cvt_pk_bf16_f32 v211, v22, v23
	v_cvt_pk_bf16_f32 v212, v16, v17
	v_cvt_pk_bf16_f32 v213, v18, v19
	global_store_dwordx4 v228, v[210:213], s[90:91] offset:256
	s_add_u32 s90, s90, 0x2000
	s_addc_u32 s91, s91, 0
	s_waitcnt vmcnt(8)
	v_lshlrev_b32_e32 v250, 16, v186
	v_and_b32_e32 v251, 0xffff0000, v186
	v_pk_mul_f32 v[44:45], v[44:45], v[250:251]
	v_lshlrev_b32_e32 v250, 16, v187
	v_and_b32_e32 v251, 0xffff0000, v187
	v_pk_mul_f32 v[46:47], v[46:47], v[250:251]
	v_lshlrev_b32_e32 v250, 16, v188
	v_and_b32_e32 v251, 0xffff0000, v188
	v_pk_mul_f32 v[40:41], v[40:41], v[250:251]
	v_lshlrev_b32_e32 v250, 16, v189
	v_and_b32_e32 v251, 0xffff0000, v189
	v_pk_mul_f32 v[42:43], v[42:43], v[250:251]
	v_cvt_pk_bf16_f32 v246, v44, v45
	v_cvt_pk_bf16_f32 v247, v46, v47
	v_cvt_pk_bf16_f32 v248, v40, v41
	v_cvt_pk_bf16_f32 v249, v42, v43
	global_store_dwordx4 v228, v[246:249], s[90:91]
	s_waitcnt vmcnt(7)
	v_lshlrev_b32_e32 v250, 16, v190
	v_and_b32_e32 v251, 0xffff0000, v190
	v_pk_mul_f32 v[12:13], v[12:13], v[250:251]
	v_lshlrev_b32_e32 v250, 16, v191
	v_and_b32_e32 v251, 0xffff0000, v191
	v_pk_mul_f32 v[14:15], v[14:15], v[250:251]
	v_lshlrev_b32_e32 v250, 16, v192
	v_and_b32_e32 v251, 0xffff0000, v192
	v_pk_mul_f32 v[8:9], v[8:9], v[250:251]
	v_lshlrev_b32_e32 v250, 16, v193
	v_and_b32_e32 v251, 0xffff0000, v193
	v_pk_mul_f32 v[10:11], v[10:11], v[250:251]
	v_cvt_pk_bf16_f32 v210, v12, v13
	v_cvt_pk_bf16_f32 v211, v14, v15
	v_cvt_pk_bf16_f32 v212, v8, v9
	v_cvt_pk_bf16_f32 v213, v10, v11
	global_store_dwordx4 v228, v[210:213], s[90:91] offset:256
	s_branch .LBB0_422
.Lepi6:
	s_cmp_eq_u32 s70, 0
	s_cbranch_scc1 .Lepi6z
	v_lshlrev_b32_e32 v228, 9, v184
	v_lshl_add_u32 v228, v150, 1, v228
	v_readlane_b32 s74, v252, 54
	v_readlane_b32 s75, v252, 55
	v_readlane_b32 s76, v252, 56
	v_readlane_b32 s77, v252, 57
	s_cmp_lt_i32 s70, 2
	s_cbranch_scc0 .Lepi6_out
	v_mov_b32_e32 v229, v228
	s_mov_b32 s78, s76
	s_mov_b32 s79, s77
	s_mov_b32 s80, 0x10000
	s_movk_i32 s81, 0x2000
	s_branch .Lepi6_go
